# weight-conversion tiles: all 8 row loads issued before the first wait (compiler had one dependent round trip per row)
# speedup vs baseline: 1.0693x; 1.0102x over previous
.LBB0_257:
	s_lshr_b32 s20, s24, 8
	v_cvt_f32_u32_e32 v0, s20
	s_sub_i32 s42, 0, s20
	s_abs_i32 s37, s36
	s_ashr_i32 s21, s36, 31
	v_rcp_iflag_f32_e32 v0, v0
	v_ashrrev_i32_e32 v20, 6, v236
	s_barrier
	v_mul_f32_e32 v0, 0x4f7ffffe, v0
	v_cvt_u32_f32_e32 v0, v0
	v_lshlrev_b32_e32 v22, 2, v236
	v_readlane_b32 s72, v252, 20
	v_readfirstlane_b32 s43, v0
	s_mul_i32 s42, s42, s43
	s_mul_hi_u32 s42, s43, s42
	s_add_i32 s43, s43, s42
	s_mul_hi_u32 s42, s37, s43
	s_mul_i32 s43, s42, s20
	s_sub_i32 s37, s37, s43
	s_add_i32 s43, s42, 1
	s_sub_i32 s81, s37, s20
	s_cmp_ge_u32 s37, s20
	s_cselect_b32 s42, s43, s42
	s_cselect_b32 s37, s81, s37
	s_add_i32 s43, s42, 1
	s_cmp_ge_u32 s37, s20
	s_cselect_b32 s37, s43, s42
	s_xor_b32 s37, s37, s21
	s_sub_i32 s21, s37, s21
	s_mul_i32 s20, s21, s20
	s_sub_i32 s20, s36, s20
	s_lshl_b32 s36, s20, 8
	s_lshl_b32 s20, s21, 5
	v_add_u32_e32 v0, s20, v20
	s_waitcnt lgkmcnt(0)
	v_mad_u64_u32 v[2:3], s[42:43], v0, s24, 0
	v_ashrrev_i32_e32 v4, 31, v0
	v_mov_b32_e32 v0, v3
	v_mad_u64_u32 v[4:5], s[42:43], v4, s24, v[0:1]
	v_mov_b32_e32 v3, v4
	v_lshl_add_u64 v[2:3], v[2:3], 2, s[30:31]
	s_ashr_i32 s37, s36, 31
	v_lshlrev_b32_e32 v0, 4, v236
	v_lshl_add_u64 v[2:3], s[36:37], 2, v[2:3]
	v_and_b32_e32 v0, 0x3f0, v0
	v_mul_u32_u24_e64 v4, s24, 12
	v_lshl_add_u64 v[2:3], v[2:3], 0, v[0:1]
	v_lshlrev_b32_e32 v4, 2, v4
	v_mov_b32_e32 v5, v1
	v_lshl_add_u64 v[10:11], v[2:3], 0, v[4:5]
	v_mul_u32_u24_e64 v4, s24, 20
	v_lshlrev_b32_e32 v4, 2, v4
	v_lshl_add_u64 v[14:15], v[2:3], 0, v[4:5]
	v_mul_u32_u24_e64 v4, s24, 24
	s_lshl_b32 s94, s24, 2
	v_lshlrev_b32_e32 v4, 2, v4
	v_lshl_add_u64 v[6:7], s[94:95], 2, v[2:3]
	s_lshl_b32 s94, s24, 3
	v_lshl_add_u64 v[16:17], v[2:3], 0, v[4:5]
	v_mul_u32_u24_e64 v4, s24, 28
	v_lshl_add_u64 v[8:9], s[94:95], 2, v[2:3]
	s_lshl_b32 s94, s24, 4
	v_lshlrev_b32_e32 v4, 2, v4
	v_lshl_add_u64 v[12:13], s[94:95], 2, v[2:3]
	v_lshl_add_u64 v[18:19], v[2:3], 0, v[4:5]
	global_load_dwordx4 v[40:43], v[2:3], off
	global_load_dwordx4 v[44:47], v[6:7], off
	global_load_dwordx4 v[48:51], v[8:9], off
	global_load_dwordx4 v[52:55], v[10:11], off
	global_load_dwordx4 v[56:59], v[12:13], off
	global_load_dwordx4 v[60:63], v[14:15], off
	global_load_dwordx4 v[64:67], v[16:17], off
	global_load_dwordx4 v[68:71], v[18:19], off
	s_movk_i32 s21, 0x410
	v_mad_u64_u32 v[20:21], s[30:31], v20, s21, v[0:1]
	s_ashr_i32 s21, s20, 31
	s_mov_b32 s81, s1
	v_readlane_b32 s73, v252, 21
	s_waitcnt vmcnt(7)
	ds_write_b128 v20, v[40:43]
	s_waitcnt vmcnt(6)
	ds_write_b128 v20, v[44:47] offset:4160
	s_waitcnt vmcnt(5)
	ds_write_b128 v20, v[48:51] offset:8320
	s_waitcnt vmcnt(4)
	ds_write_b128 v20, v[52:55] offset:12480
	s_waitcnt vmcnt(3)
	ds_write_b128 v20, v[56:59] offset:16640
	s_waitcnt vmcnt(2)
	ds_write_b128 v20, v[60:63] offset:20800
	s_waitcnt vmcnt(1)
	ds_write_b128 v20, v[64:67] offset:24960
	s_waitcnt vmcnt(0)
	ds_write_b128 v20, v[68:71] offset:29120
	v_add_u32_e32 v2, s36, v236
	v_ashrrev_i32_e32 v3, 31, v2
	v_mul_lo_u32 v6, s4, v3
	v_mul_lo_u32 v7, s5, v2
	v_mad_u64_u32 v[2:3], s[4:5], s4, v2, 0
	s_waitcnt lgkmcnt(0)
	s_barrier
	ds_read_b32 v0, v22
	ds_read_b32 v4, v22 offset:1040
	ds_read_b32 v5, v22 offset:2080
	ds_read_b32 v8, v22 offset:3120
	ds_read_b32 v9, v22 offset:4160
	ds_read_b32 v10, v22 offset:5200
	ds_read_b32 v11, v22 offset:6240
	ds_read_b32 v12, v22 offset:7280
	ds_read_b32 v13, v22 offset:8320
	ds_read_b32 v14, v22 offset:9360
	ds_read_b32 v15, v22 offset:10400
	ds_read_b32 v16, v22 offset:11440
	ds_read_b32 v17, v22 offset:12480
	ds_read_b32 v18, v22 offset:13520
	ds_read_b32 v19, v22 offset:14560
	ds_read_b32 v20, v22 offset:15600
	ds_read_b32 v21, v22 offset:16640
	ds_read_b32 v23, v22 offset:17680
	ds_read_b32 v24, v22 offset:18720
	ds_read_b32 v25, v22 offset:19760
	ds_read_b32 v26, v22 offset:20800
	ds_read_b32 v27, v22 offset:21840
	ds_read_b32 v28, v22 offset:22880
	ds_read_b32 v29, v22 offset:23920
	ds_read_b32 v30, v22 offset:24960
	ds_read_b32 v31, v22 offset:26000
	ds_read_b32 v32, v22 offset:27040
	ds_read_b32 v33, v22 offset:28080
	ds_read_b32 v34, v22 offset:29120
	ds_read_b32 v35, v22 offset:30160
	ds_read_b32 v36, v22 offset:31200
	ds_read_b32 v22, v22 offset:32240
	v_add3_u32 v3, v3, v6, v7
	v_lshl_add_u64 v[2:3], v[2:3], 1, s[26:27]
	v_lshl_add_u64 v[6:7], s[20:21], 1, v[2:3]
	s_waitcnt lgkmcnt(14)
	v_cvt_pk_bf16_f32 v2, v0, v4
	v_cvt_pk_bf16_f32 v3, v5, v8
	v_cvt_pk_bf16_f32 v4, v9, v10
	v_cvt_pk_bf16_f32 v5, v11, v12
	global_store_dwordx4 v[6:7], v[2:5], off
	s_mov_b64 s[4:5], 0
	s_nop 0
	v_cvt_pk_bf16_f32 v2, v13, v14
	v_cvt_pk_bf16_f32 v3, v15, v16
	v_cvt_pk_bf16_f32 v4, v17, v18
	v_cvt_pk_bf16_f32 v5, v19, v20
	global_store_dwordx4 v[6:7], v[2:5], off offset:16
	s_nop 1
	v_cvt_pk_bf16_f32 v2, v21, v23
	s_waitcnt lgkmcnt(12)
	v_cvt_pk_bf16_f32 v3, v24, v25
	s_waitcnt lgkmcnt(10)
	v_cvt_pk_bf16_f32 v4, v26, v27
	s_waitcnt lgkmcnt(8)
	v_cvt_pk_bf16_f32 v5, v28, v29
	global_store_dwordx4 v[6:7], v[2:5], off offset:32
	s_waitcnt lgkmcnt(6)
	s_nop 0
	v_cvt_pk_bf16_f32 v2, v30, v31
	s_waitcnt lgkmcnt(4)
	v_cvt_pk_bf16_f32 v3, v32, v33
	s_waitcnt lgkmcnt(2)
	v_cvt_pk_bf16_f32 v4, v34, v35
	s_waitcnt lgkmcnt(0)
	v_cvt_pk_bf16_f32 v5, v36, v22
	global_store_dwordx4 v[6:7], v[2:5], off offset:48

.LBB0_426:
	s_lshr_b32 s28, s24, 8
	v_cvt_f32_u32_e32 v0, s28
	s_sub_i32 s5, 0, s28
	s_add_i32 s25, s75, s25
	v_ashrrev_i32_e32 v4, 6, v152
	v_rcp_iflag_f32_e32 v0, v0
	s_barrier
	v_mul_f32_e32 v0, 0x4f7ffffe, v0
	v_cvt_u32_f32_e32 v0, v0
	v_lshlrev_b32_e32 v22, 2, v152
	v_readfirstlane_b32 s29, v0
	s_mul_i32 s5, s5, s29
	s_mul_hi_u32 s5, s29, s5
	s_add_i32 s29, s29, s5
	s_mul_hi_u32 s5, s25, s29
	s_mul_i32 s29, s5, s28
	s_sub_i32 s29, s25, s29
	s_add_i32 s30, s5, 1
	s_sub_i32 s31, s29, s28
	s_cmp_ge_u32 s29, s28
	s_cselect_b32 s5, s30, s5
	s_cselect_b32 s29, s31, s29
	s_add_i32 s30, s5, 1
	s_cmp_ge_u32 s29, s28
	s_cselect_b32 s5, s30, s5
	s_mul_i32 s28, s5, s28
	v_lshl_add_u32 v0, s5, 5, v4
	s_sub_i32 s25, s25, s28
	v_mad_i64_i32 v[2:3], s[28:29], v0, s24, 0
	s_lshl_b32 s94, s25, 8
	v_lshl_add_u64 v[2:3], v[2:3], 2, s[20:21]
	v_lshlrev_b32_e32 v0, 4, v152
	v_lshl_add_u64 v[2:3], s[94:95], 2, v[2:3]
	v_and_b32_e32 v0, 0x3f0, v0
	v_lshl_add_u64 v[2:3], v[2:3], 0, v[0:1]
	s_lshl_b32 s20, s24, 4
	s_mov_b32 s21, s95
	v_lshl_add_u64 v[6:7], v[2:3], 0, s[20:21]
	s_lshl_b32 s20, s24, 5
	v_lshl_add_u64 v[8:9], v[2:3], 0, s[20:21]
	s_mul_i32 s20, s24, 48
	v_lshl_add_u64 v[10:11], v[2:3], 0, s[20:21]
	s_lshl_b32 s20, s24, 6
	v_lshl_add_u64 v[12:13], v[2:3], 0, s[20:21]
	s_mul_i32 s20, s24, 0x50
	v_lshl_add_u64 v[14:15], v[2:3], 0, s[20:21]
	s_mul_i32 s20, s24, 0x60
	v_lshl_add_u64 v[16:17], v[2:3], 0, s[20:21]
	s_mul_i32 s20, s24, 0x70
	v_lshl_add_u64 v[18:19], v[2:3], 0, s[20:21]
	s_movk_i32 s20, 0x410
	v_mad_u64_u32 v[20:21], s[20:21], v4, s20, v[0:1]
	global_load_dwordx4 v[40:43], v[2:3], off
	global_load_dwordx4 v[44:47], v[6:7], off
	global_load_dwordx4 v[48:51], v[8:9], off
	global_load_dwordx4 v[52:55], v[10:11], off
	global_load_dwordx4 v[56:59], v[12:13], off
	global_load_dwordx4 v[60:63], v[14:15], off
	global_load_dwordx4 v[64:67], v[16:17], off
	global_load_dwordx4 v[68:71], v[18:19], off
	s_waitcnt vmcnt(7)
	ds_write_b128 v20, v[40:43]
	s_waitcnt vmcnt(6)
	ds_write_b128 v20, v[44:47] offset:4160
	s_waitcnt vmcnt(5)
	ds_write_b128 v20, v[48:51] offset:8320
	s_waitcnt vmcnt(4)
	ds_write_b128 v20, v[52:55] offset:12480
	s_waitcnt vmcnt(3)
	ds_write_b128 v20, v[56:59] offset:16640
	s_waitcnt vmcnt(2)
	ds_write_b128 v20, v[60:63] offset:20800
	s_waitcnt vmcnt(1)
	ds_write_b128 v20, v[64:67] offset:24960
	s_waitcnt vmcnt(0)
	ds_write_b128 v20, v[68:71] offset:29120
	v_add_u32_e32 v2, s94, v152
	s_waitcnt lgkmcnt(0)
	s_barrier
	ds_read_b32 v0, v22
	ds_read_b32 v4, v22 offset:1040
	ds_read_b32 v5, v22 offset:2080
	ds_read_b32 v8, v22 offset:3120
	ds_read_b32 v9, v22 offset:4160
	ds_read_b32 v10, v22 offset:5200
	ds_read_b32 v11, v22 offset:6240
	ds_read_b32 v12, v22 offset:7280
	ds_read_b32 v13, v22 offset:8320
	ds_read_b32 v14, v22 offset:9360
	ds_read_b32 v15, v22 offset:10400
	ds_read_b32 v16, v22 offset:11440
	ds_read_b32 v17, v22 offset:12480
	ds_read_b32 v18, v22 offset:13520
	ds_read_b32 v19, v22 offset:14560
	ds_read_b32 v20, v22 offset:15600
	ds_read_b32 v21, v22 offset:16640
	ds_read_b32 v23, v22 offset:17680
	ds_read_b32 v24, v22 offset:18720
	ds_read_b32 v25, v22 offset:19760
	ds_read_b32 v26, v22 offset:20800
	ds_read_b32 v27, v22 offset:21840
	ds_read_b32 v28, v22 offset:22880
	ds_read_b32 v29, v22 offset:23920
	ds_read_b32 v30, v22 offset:24960
	ds_read_b32 v31, v22 offset:26000
	ds_read_b32 v32, v22 offset:27040
	ds_read_b32 v33, v22 offset:28080
	ds_read_b32 v34, v22 offset:29120
	ds_read_b32 v35, v22 offset:30160
	ds_read_b32 v36, v22 offset:31200
	ds_read_b32 v22, v22 offset:32240
	v_mad_i64_i32 v[2:3], s[20:21], s4, v2, 0
	v_lshl_add_u64 v[2:3], v[2:3], 1, s[26:27]
	s_lshl_b32 s94, s5, 6
	v_lshl_add_u64 v[6:7], v[2:3], 0, s[94:95]
	s_waitcnt lgkmcnt(14)
	v_cvt_pk_bf16_f32 v2, v0, v4
	v_cvt_pk_bf16_f32 v3, v5, v8
	v_cvt_pk_bf16_f32 v4, v9, v10
	v_cvt_pk_bf16_f32 v5, v11, v12
	global_store_dwordx4 v[6:7], v[2:5], off
	s_mov_b64 s[4:5], 0
	s_nop 0
	v_cvt_pk_bf16_f32 v2, v13, v14
	v_cvt_pk_bf16_f32 v3, v15, v16
	v_cvt_pk_bf16_f32 v4, v17, v18
	v_cvt_pk_bf16_f32 v5, v19, v20
	global_store_dwordx4 v[6:7], v[2:5], off offset:16
	s_nop 1
	v_cvt_pk_bf16_f32 v2, v21, v23
	s_waitcnt lgkmcnt(12)
	v_cvt_pk_bf16_f32 v3, v24, v25
	s_waitcnt lgkmcnt(10)
	v_cvt_pk_bf16_f32 v4, v26, v27
	s_waitcnt lgkmcnt(8)
	v_cvt_pk_bf16_f32 v5, v28, v29
	global_store_dwordx4 v[6:7], v[2:5], off offset:32
	s_waitcnt lgkmcnt(6)
	s_nop 0
	v_cvt_pk_bf16_f32 v2, v30, v31
	s_waitcnt lgkmcnt(4)
	v_cvt_pk_bf16_f32 v3, v32, v33
	s_waitcnt lgkmcnt(2)
	v_cvt_pk_bf16_f32 v4, v34, v35
	s_waitcnt lgkmcnt(0)
	v_cvt_pk_bf16_f32 v5, v36, v22
	global_store_dwordx4 v[6:7], v[2:5], off offset:48

.LBB0_529:
	v_mov_b32_e32 v0, v1
	s_mov_b64 s[20:21], -1
	v_mbcnt_lo_u32_b32 v0, -1, v0
	v_mbcnt_hi_u32_b32 v0, -1, v0
	s_waitcnt lgkmcnt(0)
	v_add_u32_e32 v4, s80, v0
	s_cmpk_gt_i32 s29, 0x7ff
	v_ashrrev_i32_e32 v3, 6, v4
	v_lshlrev_b32_e32 v2, 2, v4
	s_cbranch_scc0 .LBB0_531
	s_add_i32 s20, s29, 0xf800
	s_and_b32 s31, s20, 0xffe0
	v_add_u32_e32 v6, s31, v3
	v_ashrrev_i32_e32 v7, 31, v6
	v_readlane_b32 s52, v253, 8
	s_and_b32 s30, s25, 0x1f00
	v_lshlrev_b64 v[6:7], 15, v[6:7]
	v_readlane_b32 s54, v253, 10
	v_readlane_b32 s55, v253, 11
	s_lshl_b32 s94, s30, 2
	v_lshlrev_b32_e32 v0, 4, v4
	v_lshl_add_u64 v[6:7], s[54:55], 0, v[6:7]
	v_lshl_add_u64 v[6:7], v[6:7], 0, s[94:95]
	v_and_b32_e32 v0, 0x3f0, v0
	v_lshl_add_u64 v[10:11], v[6:7], 0, v[0:1]
	s_waitcnt lgkmcnt(0)
	s_barrier
	global_load_dwordx4 v[6:9], v[10:11], off
	s_movk_i32 s20, 0x410
	v_mad_u64_u32 v[12:13], s[20:21], v3, s20, v[0:1]
	s_mov_b32 s20, 0x20000
	v_readlane_b32 s53, v253, 9
	v_readlane_b32 s56, v253, 12
	v_readlane_b32 s57, v253, 13
	v_readlane_b32 s58, v253, 14
	v_readlane_b32 s59, v253, 15
	v_readlane_b32 s60, v253, 16
	v_readlane_b32 s61, v253, 17
	v_readlane_b32 s62, v253, 18
	v_readlane_b32 s63, v253, 19
	v_add_u32_e32 v4, s30, v4
	v_ashrrev_i32_e32 v5, 31, v4
	v_readlane_b32 s48, v252, 4
	v_lshlrev_b64 v[4:5], 11, v[4:5]
	v_readlane_b32 s62, v252, 18
	v_readlane_b32 s63, v252, 19
	s_lshl_b32 s94, s31, 1
	v_readlane_b32 s64, v253, 20
	v_lshl_add_u64 v[4:5], s[62:63], 0, v[4:5]
	v_readlane_b32 s65, v253, 21
	v_readlane_b32 s66, v253, 22
	v_readlane_b32 s67, v253, 23
	v_readlane_b32 s42, v254, 38
	v_readlane_b32 s49, v252, 5
	v_readlane_b32 s50, v252, 6
	v_readlane_b32 s51, v252, 7
	v_readlane_b32 s52, v252, 8
	v_readlane_b32 s53, v252, 9
	v_readlane_b32 s54, v252, 10
	v_readlane_b32 s55, v252, 11
	v_readlane_b32 s56, v252, 12
	v_readlane_b32 s57, v252, 13
	v_readlane_b32 s58, v252, 14
	v_readlane_b32 s59, v252, 15
	v_readlane_b32 s60, v252, 16
	v_readlane_b32 s61, v252, 17
	v_add_co_u32_e32 v14, vcc, 0x20000, v10
	s_nop 1
	v_addc_co_u32_e32 v15, vcc, 0, v11, vcc
	global_load_dwordx4 v[14:17], v[14:15], off
	v_add_co_u32_e32 v18, vcc, 0x40000, v10
	s_nop 1
	v_addc_co_u32_e32 v19, vcc, 0, v11, vcc
	global_load_dwordx4 v[18:21], v[18:19], off
	v_add_co_u32_e32 v22, vcc, 0x60000, v10
	s_nop 1
	v_addc_co_u32_e32 v23, vcc, 0, v11, vcc
	global_load_dwordx4 v[22:25], v[22:23], off
	v_add_co_u32_e32 v26, vcc, 0x80000, v10
	s_nop 1
	v_addc_co_u32_e32 v27, vcc, 0, v11, vcc
	global_load_dwordx4 v[26:29], v[26:27], off
	v_add_co_u32_e32 v30, vcc, 0xa0000, v10
	s_nop 1
	v_addc_co_u32_e32 v31, vcc, 0, v11, vcc
	global_load_dwordx4 v[30:33], v[30:31], off
	v_add_co_u32_e32 v34, vcc, 0xc0000, v10
	s_nop 1
	v_addc_co_u32_e32 v35, vcc, 0, v11, vcc
	global_load_dwordx4 v[34:37], v[34:35], off
	v_add_co_u32_e32 v40, vcc, 0xe0000, v10
	s_nop 1
	v_addc_co_u32_e32 v41, vcc, 0, v11, vcc
	global_load_dwordx4 v[40:43], v[40:41], off
	s_mov_b64 s[20:21], 0
	s_waitcnt vmcnt(7)
	ds_write_b128 v12, v[6:9]
	s_waitcnt vmcnt(6)
	ds_write_b128 v12, v[14:17] offset:4160
	s_waitcnt vmcnt(5)
	ds_write_b128 v12, v[18:21] offset:8320
	s_waitcnt vmcnt(4)
	ds_write_b128 v12, v[22:25] offset:12480
	s_waitcnt vmcnt(3)
	ds_write_b128 v12, v[26:29] offset:16640
	s_waitcnt vmcnt(2)
	ds_write_b128 v12, v[30:33] offset:20800
	s_waitcnt vmcnt(1)
	ds_write_b128 v12, v[34:37] offset:24960
	s_waitcnt vmcnt(0)
	ds_write_b128 v12, v[40:43] offset:29120
	s_waitcnt lgkmcnt(0)
	s_barrier
	ds_read_b32 v0, v2
	ds_read_b32 v6, v2 offset:1040
	ds_read_b32 v7, v2 offset:2080
	ds_read_b32 v10, v2 offset:3120
	ds_read_b32 v11, v2 offset:4160
	ds_read_b32 v12, v2 offset:5200
	ds_read_b32 v13, v2 offset:6240
	ds_read_b32 v14, v2 offset:7280
	ds_read_b32 v15, v2 offset:8320
	ds_read_b32 v16, v2 offset:9360
	ds_read_b32 v17, v2 offset:10400
	ds_read_b32 v18, v2 offset:11440
	ds_read_b32 v19, v2 offset:12480
	ds_read_b32 v20, v2 offset:13520
	ds_read_b32 v21, v2 offset:14560
	ds_read_b32 v22, v2 offset:15600
	ds_read_b32 v23, v2 offset:16640
	ds_read_b32 v24, v2 offset:17680
	ds_read_b32 v25, v2 offset:18720
	ds_read_b32 v26, v2 offset:19760
	ds_read_b32 v27, v2 offset:20800
	ds_read_b32 v28, v2 offset:21840
	ds_read_b32 v29, v2 offset:22880
	ds_read_b32 v30, v2 offset:23920
	ds_read_b32 v31, v2 offset:24960
	ds_read_b32 v32, v2 offset:26000
	ds_read_b32 v33, v2 offset:27040
	ds_read_b32 v34, v2 offset:28080
	ds_read_b32 v35, v2 offset:29120
	ds_read_b32 v36, v2 offset:30160
	ds_read_b32 v37, v2 offset:31200
	ds_read_b32 v38, v2 offset:32240
	v_lshl_add_u64 v[8:9], v[4:5], 0, s[94:95]
	s_waitcnt lgkmcnt(14)
	v_cvt_pk_bf16_f32 v4, v0, v6
	v_cvt_pk_bf16_f32 v5, v7, v10
	v_cvt_pk_bf16_f32 v6, v11, v12
	v_cvt_pk_bf16_f32 v7, v13, v14
	global_store_dwordx4 v[8:9], v[4:7], off
	s_nop 1
	v_cvt_pk_bf16_f32 v4, v15, v16
	v_cvt_pk_bf16_f32 v5, v17, v18
	v_cvt_pk_bf16_f32 v6, v19, v20
	v_cvt_pk_bf16_f32 v7, v21, v22
	global_store_dwordx4 v[8:9], v[4:7], off offset:16
	s_nop 1
	v_cvt_pk_bf16_f32 v4, v23, v24
	s_waitcnt lgkmcnt(12)
	v_cvt_pk_bf16_f32 v5, v25, v26
	s_waitcnt lgkmcnt(10)
	v_cvt_pk_bf16_f32 v6, v27, v28
	s_waitcnt lgkmcnt(8)
	v_cvt_pk_bf16_f32 v7, v29, v30
	global_store_dwordx4 v[8:9], v[4:7], off offset:32
	s_waitcnt lgkmcnt(6)
	s_nop 0
	v_cvt_pk_bf16_f32 v4, v31, v32
	s_waitcnt lgkmcnt(4)
	v_cvt_pk_bf16_f32 v5, v33, v34
	s_waitcnt lgkmcnt(2)
	v_cvt_pk_bf16_f32 v6, v35, v36
	s_waitcnt lgkmcnt(0)
	v_cvt_pk_bf16_f32 v7, v37, v38
	global_store_dwordx4 v[8:9], v[4:7], off offset:48
